# combo12 = combo9 + GEMM K-loop heads aligned to 256 bytes
# baseline (speedup 1.0000x reference)
;     __device__ __forceinline__ bool next(int i, Unit& u) const { if (i != 0 || c >= 8) return false; u.pm = c >> 2; u.pn = c; return true; }
; template <class Epi, class Sched, bool ALIGN_EPI = false, bool SP2 = false>
; __device__ __forceinline__ void gemm_phase(PG8_LAS unsigned char* lds, const Gemm g, const Sched& S, const Epi& E) {
;     ...
;         const bool has_next = S.next(ui + 1, nxt);
;         const char* nA = has_next ? (const char*)g.A + (size_t)nxt.pm * tstep : cA; const char* nB = has_next ? (const char*)g.Bt + (size_t)nxt.pn * tstep : cB;
;         for (int t = 0; t < nt; t += 2) {
;             const bool last = (t == nt - 2);
;             const char* a1 = cA + (size_t)(t + 1) * kstep;
;             const char* a2 = last ? nA : cA + (size_t)(t + 2) * kstep; const char* b2 = last ? nB : cB + (size_t)(t + 2) * kstep;
;             const char* a3 = a2 + kstep; const char* b3 = b2 + kstep;
;     ...
; #pragma unroll
;         for (int a = 0; a < 2; ++a)
; #pragma unroll
;             for (int b = 0; b < 2; ++b)
; #pragma unroll
;                 for (int m = 0; m < 4; ++m)
; #pragma unroll
;                     for (int n = 0; n < 2; ++n) acc[a][b][m][n] = (f32x4){0.f, 0.f, 0.f, 0.f};
;         cur = nxt; cA = nA; cB = nB; ++ui;
.LBB0_423:
	s_ashr_i32 s29, s28, 31
	s_lshl_b64 s[0:1], s[28:29], 20
	s_add_u32 s60, s88, s0
	s_addc_u32 s61, s89, s1
	s_and_b64 s[0:1], s[6:7], exec
	s_cselect_b32 s14, s61, s67
	s_cselect_b32 s15, s60, s66
	s_ashr_i32 s95, s94, 31
	s_lshl_b64 s[0:1], s[94:95], 20
	s_add_u32 s0, s21, s0
	s_addc_u32 s1, s22, s1
	s_and_b64 s[16:17], s[6:7], exec
	s_cselect_b32 s16, s1, s9
	s_cselect_b32 s17, s0, s8
	s_add_u32 s18, s8, 0x100
	s_addc_u32 s19, s9, 0
	s_add_u32 s8, s66, 0x80080
	v_mov_b32_e32 v0, 0
	s_addc_u32 s9, s67, 0
	s_mov_b32 s29, -2
	v_mov_b32_e32 v1, v0
	v_mov_b32_e32 v2, v0
	v_mov_b32_e32 v3, v0
	v_mov_b32_e32 v4, v0
	v_mov_b32_e32 v5, v0
	v_mov_b32_e32 v6, v0
	v_mov_b32_e32 v7, v0
	v_mov_b32_e32 v12, v0
	v_mov_b32_e32 v13, v0
	v_mov_b32_e32 v14, v0
	v_mov_b32_e32 v15, v0
	v_mov_b32_e32 v20, v0
	v_mov_b32_e32 v21, v0
	v_mov_b32_e32 v22, v0
	v_mov_b32_e32 v23, v0
	v_mov_b32_e32 v28, v0
	v_mov_b32_e32 v29, v0
	v_mov_b32_e32 v30, v0
	v_mov_b32_e32 v31, v0
	v_mov_b32_e32 v36, v0
	v_mov_b32_e32 v37, v0
	v_mov_b32_e32 v38, v0
	v_mov_b32_e32 v39, v0
	v_mov_b32_e32 v48, v0
	v_mov_b32_e32 v49, v0
	v_mov_b32_e32 v50, v0
	v_mov_b32_e32 v51, v0
	v_mov_b32_e32 v56, v0
	v_mov_b32_e32 v57, v0
	v_mov_b32_e32 v58, v0
	v_mov_b32_e32 v59, v0
	v_mov_b32_e32 v8, v0
	v_mov_b32_e32 v9, v0
	v_mov_b32_e32 v10, v0
	v_mov_b32_e32 v11, v0
	v_mov_b32_e32 v16, v0
	v_mov_b32_e32 v17, v0
	v_mov_b32_e32 v18, v0
	v_mov_b32_e32 v19, v0
	v_mov_b32_e32 v24, v0
	v_mov_b32_e32 v25, v0
	v_mov_b32_e32 v26, v0
	v_mov_b32_e32 v27, v0
	v_mov_b32_e32 v32, v0
	v_mov_b32_e32 v33, v0
	v_mov_b32_e32 v34, v0
	v_mov_b32_e32 v35, v0
	v_mov_b32_e32 v44, v0
	v_mov_b32_e32 v45, v0
	v_mov_b32_e32 v46, v0
	v_mov_b32_e32 v47, v0
	v_mov_b32_e32 v52, v0
	v_mov_b32_e32 v53, v0
	v_mov_b32_e32 v54, v0
	v_mov_b32_e32 v55, v0
	v_mov_b32_e32 v60, v0
	v_mov_b32_e32 v61, v0
	v_mov_b32_e32 v62, v0
	v_mov_b32_e32 v63, v0
	v_mov_b32_e32 v64, v0
	v_mov_b32_e32 v65, v0
	v_mov_b32_e32 v66, v0
	v_mov_b32_e32 v67, v0
	v_mov_b32_e32 v68, v0
	v_mov_b32_e32 v69, v0
	v_mov_b32_e32 v70, v0
	v_mov_b32_e32 v71, v0
	v_mov_b32_e32 v72, v0
	v_mov_b32_e32 v73, v0
	v_mov_b32_e32 v74, v0
	v_mov_b32_e32 v75, v0
	v_mov_b32_e32 v80, v0
	v_mov_b32_e32 v81, v0
	v_mov_b32_e32 v82, v0
	v_mov_b32_e32 v83, v0
	v_mov_b32_e32 v88, v0
	v_mov_b32_e32 v89, v0
	v_mov_b32_e32 v90, v0
	v_mov_b32_e32 v91, v0
	v_mov_b32_e32 v96, v0
	v_mov_b32_e32 v97, v0
	v_mov_b32_e32 v98, v0
	v_mov_b32_e32 v99, v0
	v_mov_b32_e32 v104, v0
	v_mov_b32_e32 v105, v0
	v_mov_b32_e32 v106, v0
	v_mov_b32_e32 v107, v0
	v_mov_b32_e32 v112, v0
	v_mov_b32_e32 v113, v0
	v_mov_b32_e32 v114, v0
	v_mov_b32_e32 v115, v0
	v_mov_b32_e32 v120, v0
	v_mov_b32_e32 v121, v0
	v_mov_b32_e32 v122, v0
	v_mov_b32_e32 v123, v0
	v_mov_b32_e32 v76, v0
	v_mov_b32_e32 v77, v0
	v_mov_b32_e32 v78, v0
	v_mov_b32_e32 v79, v0
	v_mov_b32_e32 v84, v0
	v_mov_b32_e32 v85, v0
	v_mov_b32_e32 v86, v0
	v_mov_b32_e32 v87, v0
	v_mov_b32_e32 v92, v0
	v_mov_b32_e32 v93, v0
	v_mov_b32_e32 v94, v0
	v_mov_b32_e32 v95, v0
	v_mov_b32_e32 v100, v0
	v_mov_b32_e32 v101, v0
	v_mov_b32_e32 v102, v0
	v_mov_b32_e32 v103, v0
	v_mov_b32_e32 v108, v0
	v_mov_b32_e32 v109, v0
	v_mov_b32_e32 v110, v0
	v_mov_b32_e32 v111, v0
	v_mov_b32_e32 v116, v0
	v_mov_b32_e32 v117, v0
	v_mov_b32_e32 v118, v0
	v_mov_b32_e32 v119, v0
	v_mov_b32_e32 v124, v0
	v_mov_b32_e32 v125, v0
	v_mov_b32_e32 v126, v0
	v_mov_b32_e32 v127, v0
	v_mov_b32_e32 v130, v0
	v_mov_b32_e32 v131, v0
	v_mov_b32_e32 v132, v0
	v_mov_b32_e32 v133, v0
	.p2align	8

;     __device__ __forceinline__ bool next(int i, Unit& u) const { if (i != 0 || c >= 8) return false; u.pm = c >> 2; u.pn = c; return true; }
; template <class Epi, class Sched, bool ALIGN_EPI = false, bool SP2 = false>
; __device__ __forceinline__ void gemm_phase(PG8_LAS unsigned char* lds, const Gemm g, const Sched& S, const Epi& E) {
;     ...
;         const bool has_next = S.next(ui + 1, nxt);
;         const char* nA = has_next ? (const char*)g.A + (size_t)nxt.pm * tstep : cA; const char* nB = has_next ? (const char*)g.Bt + (size_t)nxt.pn * tstep : cB;
;         for (int t = 0; t < nt; t += 2) {
;             const bool last = (t == nt - 2);
;             const char* a1 = cA + (size_t)(t + 1) * kstep;
;             const char* a2 = last ? nA : cA + (size_t)(t + 2) * kstep; const char* b2 = last ? nB : cB + (size_t)(t + 2) * kstep;
;             const char* a3 = a2 + kstep; const char* b3 = b2 + kstep;
;     ...
; #pragma unroll
;         for (int a = 0; a < 2; ++a)
; #pragma unroll
;             for (int b = 0; b < 2; ++b)
; #pragma unroll
;                 for (int m = 0; m < 4; ++m)
; #pragma unroll
;                     for (int n = 0; n < 2; ++n) acc[a][b][m][n] = (f32x4){0.f, 0.f, 0.f, 0.f};
;         cur = nxt; cA = nA; cB = nB; ++ui;
.LBB0_457:
	s_add_u32 s13, s66, 0x100
	s_addc_u32 s91, s67, 0
	s_add_u32 s10, s96, 0x80
	v_mov_b32_e32 v0, 0
	s_addc_u32 s11, s97, 0
	s_mov_b32 s66, 0
	v_mov_b32_e32 v1, v0
	v_mov_b32_e32 v2, v0
	v_mov_b32_e32 v3, v0
	v_mov_b32_e32 v4, v0
	v_mov_b32_e32 v5, v0
	v_mov_b32_e32 v6, v0
	v_mov_b32_e32 v7, v0
	v_mov_b32_e32 v16, v0
	v_mov_b32_e32 v17, v0
	v_mov_b32_e32 v18, v0
	v_mov_b32_e32 v19, v0
	v_mov_b32_e32 v20, v0
	v_mov_b32_e32 v21, v0
	v_mov_b32_e32 v22, v0
	v_mov_b32_e32 v23, v0
	v_mov_b32_e32 v32, v0
	v_mov_b32_e32 v33, v0
	v_mov_b32_e32 v34, v0
	v_mov_b32_e32 v35, v0
	v_mov_b32_e32 v36, v0
	v_mov_b32_e32 v37, v0
	v_mov_b32_e32 v38, v0
	v_mov_b32_e32 v39, v0
	v_mov_b32_e32 v52, v0
	v_mov_b32_e32 v53, v0
	v_mov_b32_e32 v54, v0
	v_mov_b32_e32 v55, v0
	v_mov_b32_e32 v56, v0
	v_mov_b32_e32 v57, v0
	v_mov_b32_e32 v58, v0
	v_mov_b32_e32 v59, v0
	v_mov_b32_e32 v8, v0
	v_mov_b32_e32 v9, v0
	v_mov_b32_e32 v10, v0
	v_mov_b32_e32 v11, v0
	v_mov_b32_e32 v12, v0
	v_mov_b32_e32 v13, v0
	v_mov_b32_e32 v14, v0
	v_mov_b32_e32 v15, v0
	v_mov_b32_e32 v24, v0
	v_mov_b32_e32 v25, v0
	v_mov_b32_e32 v26, v0
	v_mov_b32_e32 v27, v0
	v_mov_b32_e32 v28, v0
	v_mov_b32_e32 v29, v0
	v_mov_b32_e32 v30, v0
	v_mov_b32_e32 v31, v0
	v_mov_b32_e32 v40, v0
	v_mov_b32_e32 v41, v0
	v_mov_b32_e32 v42, v0
	v_mov_b32_e32 v43, v0
	v_mov_b32_e32 v44, v0
	v_mov_b32_e32 v45, v0
	v_mov_b32_e32 v46, v0
	v_mov_b32_e32 v47, v0
	v_mov_b32_e32 v64, v0
	v_mov_b32_e32 v65, v0
	v_mov_b32_e32 v66, v0
	v_mov_b32_e32 v67, v0
	v_mov_b32_e32 v68, v0
	v_mov_b32_e32 v69, v0
	v_mov_b32_e32 v70, v0
	v_mov_b32_e32 v71, v0
	v_mov_b32_e32 v76, v0
	v_mov_b32_e32 v77, v0
	v_mov_b32_e32 v78, v0
	v_mov_b32_e32 v79, v0
	v_mov_b32_e32 v80, v0
	v_mov_b32_e32 v81, v0
	v_mov_b32_e32 v82, v0
	v_mov_b32_e32 v83, v0
	v_mov_b32_e32 v100, v0
	v_mov_b32_e32 v101, v0
	v_mov_b32_e32 v102, v0
	v_mov_b32_e32 v103, v0
	v_mov_b32_e32 v104, v0
	v_mov_b32_e32 v105, v0
	v_mov_b32_e32 v106, v0
	v_mov_b32_e32 v107, v0
	v_mov_b32_e32 v124, v0
	v_mov_b32_e32 v125, v0
	v_mov_b32_e32 v126, v0
	v_mov_b32_e32 v127, v0
	v_mov_b32_e32 v130, v0
	v_mov_b32_e32 v131, v0
	v_mov_b32_e32 v132, v0
	v_mov_b32_e32 v133, v0
	v_mov_b32_e32 v154, v0
	v_mov_b32_e32 v155, v0
	v_mov_b32_e32 v156, v0
	v_mov_b32_e32 v157, v0
	v_mov_b32_e32 v158, v0
	v_mov_b32_e32 v159, v0
	v_mov_b32_e32 v160, v0
	v_mov_b32_e32 v161, v0
	v_mov_b32_e32 v88, v0
	v_mov_b32_e32 v89, v0
	v_mov_b32_e32 v90, v0
	v_mov_b32_e32 v91, v0
	v_mov_b32_e32 v92, v0
	v_mov_b32_e32 v93, v0
	v_mov_b32_e32 v94, v0
	v_mov_b32_e32 v95, v0
	v_mov_b32_e32 v112, v0
	v_mov_b32_e32 v113, v0
	v_mov_b32_e32 v114, v0
	v_mov_b32_e32 v115, v0
	v_mov_b32_e32 v116, v0
	v_mov_b32_e32 v117, v0
	v_mov_b32_e32 v118, v0
	v_mov_b32_e32 v119, v0
	v_mov_b32_e32 v138, v0
	v_mov_b32_e32 v139, v0
	v_mov_b32_e32 v140, v0
	v_mov_b32_e32 v141, v0
	v_mov_b32_e32 v142, v0
	v_mov_b32_e32 v143, v0
	v_mov_b32_e32 v144, v0
	v_mov_b32_e32 v145, v0
	v_mov_b32_e32 v162, v0
	v_mov_b32_e32 v163, v0
	v_mov_b32_e32 v164, v0
	v_mov_b32_e32 v165, v0
	v_mov_b32_e32 v166, v0
	v_mov_b32_e32 v167, v0
	v_mov_b32_e32 v168, v0
	v_mov_b32_e32 v169, v0
	.p2align	8

;     __device__ __forceinline__ bool next(int i, Unit& u) const { if (i != 0 || c >= 8) return false; u.pm = c >> 2; u.pn = c; return true; }
; template <class Epi, class Sched, bool ALIGN_EPI = false, bool SP2 = false>
; __device__ __forceinline__ void gemm_phase(PG8_LAS unsigned char* lds, const Gemm g, const Sched& S, const Epi& E) {
;     ...
;         const bool has_next = S.next(ui + 1, nxt);
;         const char* nA = has_next ? (const char*)g.A + (size_t)nxt.pm * tstep : cA; const char* nB = has_next ? (const char*)g.Bt + (size_t)nxt.pn * tstep : cB;
;         for (int t = 0; t < nt; t += 2) {
;             const bool last = (t == nt - 2);
;             const char* a1 = cA + (size_t)(t + 1) * kstep;
;             const char* a2 = last ? nA : cA + (size_t)(t + 2) * kstep; const char* b2 = last ? nB : cB + (size_t)(t + 2) * kstep;
;             const char* a3 = a2 + kstep; const char* b3 = b2 + kstep;
;     ...
; #pragma unroll
;         for (int a = 0; a < 2; ++a)
; #pragma unroll
;             for (int b = 0; b < 2; ++b)
; #pragma unroll
;                 for (int m = 0; m < 4; ++m)
; #pragma unroll
;                     for (int n = 0; n < 2; ++n) acc[a][b][m][n] = (f32x4){0.f, 0.f, 0.f, 0.f};
;         cur = nxt; cA = nA; cB = nB; ++ui;
.LBB0_589:
	s_ashr_i32 s65, s64, 31
	s_lshl_b64 s[26:27], s[64:65], 20
	s_add_u32 s70, s88, s26
	s_addc_u32 s71, s89, s27
	s_and_b64 s[26:27], s[6:7], exec
	s_cselect_b32 s14, s71, s9
	s_cselect_b32 s26, s70, s8
	s_ashr_i32 s31, s30, 31
	s_lshl_b64 s[28:29], s[30:31], 20
	s_add_u32 s92, s17, s28
	s_addc_u32 s93, s18, s29
	s_and_b64 s[28:29], s[6:7], exec
	s_cselect_b32 s27, s93, s1
	s_cselect_b32 s31, s92, s0
	s_add_u32 s34, s0, 0x100
	s_addc_u32 s35, s1, 0
	s_add_u32 s0, s8, 0x80080
	v_mov_b32_e32 v0, 0
	s_addc_u32 s1, s9, 0
	s_mov_b32 s60, -2
	v_mov_b32_e32 v1, v0
	v_mov_b32_e32 v2, v0
	v_mov_b32_e32 v3, v0
	v_mov_b32_e32 v8, v0
	v_mov_b32_e32 v9, v0
	v_mov_b32_e32 v10, v0
	v_mov_b32_e32 v11, v0
	v_mov_b32_e32 v16, v0
	v_mov_b32_e32 v17, v0
	v_mov_b32_e32 v18, v0
	v_mov_b32_e32 v19, v0
	v_mov_b32_e32 v24, v0
	v_mov_b32_e32 v25, v0
	v_mov_b32_e32 v26, v0
	v_mov_b32_e32 v27, v0
	v_mov_b32_e32 v32, v0
	v_mov_b32_e32 v33, v0
	v_mov_b32_e32 v34, v0
	v_mov_b32_e32 v35, v0
	v_mov_b32_e32 v40, v0
	v_mov_b32_e32 v41, v0
	v_mov_b32_e32 v42, v0
	v_mov_b32_e32 v43, v0
	v_mov_b32_e32 v48, v0
	v_mov_b32_e32 v49, v0
	v_mov_b32_e32 v50, v0
	v_mov_b32_e32 v51, v0
	v_mov_b32_e32 v60, v0
	v_mov_b32_e32 v61, v0
	v_mov_b32_e32 v62, v0
	v_mov_b32_e32 v63, v0
	v_mov_b32_e32 v4, v0
	v_mov_b32_e32 v5, v0
	v_mov_b32_e32 v6, v0
	v_mov_b32_e32 v7, v0
	v_mov_b32_e32 v12, v0
	v_mov_b32_e32 v13, v0
	v_mov_b32_e32 v14, v0
	v_mov_b32_e32 v15, v0
	v_mov_b32_e32 v20, v0
	v_mov_b32_e32 v21, v0
	v_mov_b32_e32 v22, v0
	v_mov_b32_e32 v23, v0
	v_mov_b32_e32 v28, v0
	v_mov_b32_e32 v29, v0
	v_mov_b32_e32 v30, v0
	v_mov_b32_e32 v31, v0
	v_mov_b32_e32 v36, v0
	v_mov_b32_e32 v37, v0
	v_mov_b32_e32 v38, v0
	v_mov_b32_e32 v39, v0
	v_mov_b32_e32 v44, v0
	v_mov_b32_e32 v45, v0
	v_mov_b32_e32 v46, v0
	v_mov_b32_e32 v47, v0
	v_mov_b32_e32 v52, v0
	v_mov_b32_e32 v53, v0
	v_mov_b32_e32 v54, v0
	v_mov_b32_e32 v55, v0
	v_mov_b32_e32 v64, v0
	v_mov_b32_e32 v65, v0
	v_mov_b32_e32 v66, v0
	v_mov_b32_e32 v67, v0
	v_mov_b32_e32 v68, v0
	v_mov_b32_e32 v69, v0
	v_mov_b32_e32 v70, v0
	v_mov_b32_e32 v71, v0
	v_mov_b32_e32 v76, v0
	v_mov_b32_e32 v77, v0
	v_mov_b32_e32 v78, v0
	v_mov_b32_e32 v79, v0
	v_mov_b32_e32 v84, v0
	v_mov_b32_e32 v85, v0
	v_mov_b32_e32 v86, v0
	v_mov_b32_e32 v87, v0
	v_mov_b32_e32 v92, v0
	v_mov_b32_e32 v93, v0
	v_mov_b32_e32 v94, v0
	v_mov_b32_e32 v95, v0
	v_mov_b32_e32 v100, v0
	v_mov_b32_e32 v101, v0
	v_mov_b32_e32 v102, v0
	v_mov_b32_e32 v103, v0
	v_mov_b32_e32 v112, v0
	v_mov_b32_e32 v113, v0
	v_mov_b32_e32 v114, v0
	v_mov_b32_e32 v115, v0
	v_mov_b32_e32 v120, v0
	v_mov_b32_e32 v121, v0
	v_mov_b32_e32 v122, v0
	v_mov_b32_e32 v123, v0
	v_mov_b32_e32 v130, v0
	v_mov_b32_e32 v131, v0
	v_mov_b32_e32 v132, v0
	v_mov_b32_e32 v133, v0
	v_mov_b32_e32 v72, v0
	v_mov_b32_e32 v73, v0
	v_mov_b32_e32 v74, v0
	v_mov_b32_e32 v75, v0
	v_mov_b32_e32 v80, v0
	v_mov_b32_e32 v81, v0
	v_mov_b32_e32 v82, v0
	v_mov_b32_e32 v83, v0
	v_mov_b32_e32 v88, v0
	v_mov_b32_e32 v89, v0
	v_mov_b32_e32 v90, v0
	v_mov_b32_e32 v91, v0
	v_mov_b32_e32 v96, v0
	v_mov_b32_e32 v97, v0
	v_mov_b32_e32 v98, v0
	v_mov_b32_e32 v99, v0
	v_mov_b32_e32 v104, v0
	v_mov_b32_e32 v105, v0
	v_mov_b32_e32 v106, v0
	v_mov_b32_e32 v107, v0
	v_mov_b32_e32 v116, v0
	v_mov_b32_e32 v117, v0
	v_mov_b32_e32 v118, v0
	v_mov_b32_e32 v119, v0
	v_mov_b32_e32 v124, v0
	v_mov_b32_e32 v125, v0
	v_mov_b32_e32 v126, v0
	v_mov_b32_e32 v127, v0
	v_mov_b32_e32 v134, v0
	v_mov_b32_e32 v135, v0
	v_mov_b32_e32 v136, v0
	v_mov_b32_e32 v137, v0
	.p2align	8
